# G2 main K-loop: the unit's residual tile (read by the epilogue) is touched line by line during 4 of the 22 K iterations (one dword load per 128 B line) so the epilogue's reads are cache hits
# baseline (speedup 1.0000x reference)
.LBB0_535:
	s_add_u32 s56, s50, 0x100
	s_addc_u32 s57, s51, 0
	s_add_i32 s8, 0, 0x10000
	s_cmp_eq_u32 s74, 40
	s_cselect_b32 s59, s41, s57
	s_cselect_b32 s58, s40, s56
	v_add_u32_e32 v140, s8, v143
	s_cselect_b32 s55, s49, s73
	s_cselect_b32 s54, s48, s72
	s_add_i32 s10, 0, 0x14000
	ds_read_b128 v[146:149], v140
	ds_read_b128 v[150:153], v140 offset:1024
	ds_read_b128 v[154:157], v140 offset:2048
	ds_read_b128 v[158:161], v140 offset:3072
	v_add_u32_e32 v140, s10, v143
	ds_read_b128 v[162:165], v140
	ds_read_b128 v[166:169], v140 offset:1024
	ds_read_b128 v[170:173], v140 offset:2048
	ds_read_b128 v[174:177], v140 offset:3072
	v_lshl_add_u64 v[140:141], s[50:51], 0, v[136:137]
	s_add_i32 m0, s53, 0xc000
	ds_read_b128 v[178:181], v145
	ds_read_b128 v[182:185], v145 offset:1024
	ds_read_b128 v[224:227], v145 offset:2048
	ds_read_b128 v[228:231], v145 offset:3072
	ds_read_b128 v[232:235], v145 offset:4096
	ds_read_b128 v[236:239], v145 offset:5120
	ds_read_b128 v[240:243], v145 offset:6144
	ds_read_b128 v[244:247], v145 offset:7168
	global_load_lds_dwordx4 v[140:141], off
	v_lshl_add_u64 v[140:141], s[50:51], 0, v[138:139]
	s_add_i32 m0, s53, 0xe000
	s_nop 0
	global_load_lds_dwordx4 v[140:141], off
	s_waitcnt vmcnt(8)
	s_waitcnt lgkmcnt(0)
	s_barrier
	s_setprio 1
	s_waitcnt lgkmcnt(0)
	v_mfma_f32_16x16x32_bf16 v[126:129], v[146:149], v[178:181], v[126:129]
	v_mfma_f32_16x16x32_bf16 v[122:125], v[154:157], v[178:181], v[122:125]
	v_mfma_f32_16x16x32_bf16 v[110:113], v[146:149], v[224:227], v[110:113]
	v_mfma_f32_16x16x32_bf16 v[106:109], v[154:157], v[224:227], v[106:109]
	v_mfma_f32_16x16x32_bf16 v[94:97], v[146:149], v[232:235], v[94:97]
	v_mfma_f32_16x16x32_bf16 v[90:93], v[154:157], v[232:235], v[90:93]
	v_mfma_f32_16x16x32_bf16 v[78:81], v[146:149], v[240:243], v[78:81]
	v_mfma_f32_16x16x32_bf16 v[74:77], v[154:157], v[240:243], v[74:77]
	v_mfma_f32_16x16x32_bf16 v[126:129], v[150:153], v[182:185], v[126:129]
	v_mfma_f32_16x16x32_bf16 v[122:125], v[158:161], v[182:185], v[122:125]
	v_mfma_f32_16x16x32_bf16 v[110:113], v[150:153], v[228:231], v[110:113]
	v_mfma_f32_16x16x32_bf16 v[106:109], v[158:161], v[228:231], v[106:109]
	v_mfma_f32_16x16x32_bf16 v[94:97], v[150:153], v[236:239], v[94:97]
	v_mfma_f32_16x16x32_bf16 v[90:93], v[158:161], v[236:239], v[90:93]
	v_mfma_f32_16x16x32_bf16 v[78:81], v[150:153], v[244:247], v[78:81]
	v_mfma_f32_16x16x32_bf16 v[74:77], v[158:161], v[244:247], v[74:77]
	s_setprio 0
	s_setprio 1
	v_mfma_f32_16x16x32_bf16 v[118:121], v[162:165], v[178:181], v[118:121]
	v_mfma_f32_16x16x32_bf16 v[114:117], v[170:173], v[178:181], v[114:117]
	v_mfma_f32_16x16x32_bf16 v[102:105], v[162:165], v[224:227], v[102:105]
	v_mfma_f32_16x16x32_bf16 v[98:101], v[170:173], v[224:227], v[98:101]
	v_mfma_f32_16x16x32_bf16 v[86:89], v[162:165], v[232:235], v[86:89]
	v_mfma_f32_16x16x32_bf16 v[82:85], v[170:173], v[232:235], v[82:85]
	v_mfma_f32_16x16x32_bf16 v[70:73], v[162:165], v[240:243], v[70:73]
	v_mfma_f32_16x16x32_bf16 v[66:69], v[170:173], v[240:243], v[66:69]
	v_mfma_f32_16x16x32_bf16 v[118:121], v[166:169], v[182:185], v[118:121]
	v_mfma_f32_16x16x32_bf16 v[114:117], v[174:177], v[182:185], v[114:117]
	v_mfma_f32_16x16x32_bf16 v[102:105], v[166:169], v[228:231], v[102:105]
	v_mfma_f32_16x16x32_bf16 v[98:101], v[174:177], v[228:231], v[98:101]
	v_mfma_f32_16x16x32_bf16 v[86:89], v[166:169], v[236:239], v[86:89]
	v_mfma_f32_16x16x32_bf16 v[82:85], v[174:177], v[236:239], v[82:85]
	v_mfma_f32_16x16x32_bf16 v[70:73], v[166:169], v[244:247], v[70:73]
	v_mfma_f32_16x16x32_bf16 v[66:69], v[174:177], v[244:247], v[66:69]
	s_setprio 0
	s_barrier
	s_add_i32 s8, s8, s52
	v_lshl_add_u64 v[140:141], s[54:55], 0, v[0:1]
	s_mov_b32 m0, s8
	ds_read_b128 v[178:181], v145 offset:16384
	ds_read_b128 v[182:185], v145 offset:17408
	ds_read_b128 v[224:227], v145 offset:18432
	ds_read_b128 v[228:231], v145 offset:19456
	ds_read_b128 v[232:235], v145 offset:20480
	ds_read_b128 v[236:239], v145 offset:21504
	ds_read_b128 v[240:243], v145 offset:22528
	ds_read_b128 v[244:247], v145 offset:23552
	global_load_lds_dwordx4 v[140:141], off
	s_add_i32 m0, s8, 0x2000
	s_add_u32 s8, s54, 0xb0000
	v_lshl_add_u64 v[186:187], s[54:55], 0, v[130:131]
	s_addc_u32 s9, s55, 0
	s_add_i32 s10, s10, s52
	global_load_lds_dwordx4 v[186:187], off
	v_lshl_add_u64 v[202:203], s[8:9], 0, v[0:1]
	s_mov_b32 m0, s10
	v_lshl_add_u64 v[248:249], s[58:59], 0, v[132:133]
	global_load_lds_dwordx4 v[202:203], off
	v_lshl_add_u64 v[202:203], s[8:9], 0, v[130:131]
	s_add_i32 m0, s10, 0x2000
	s_nop 0
	global_load_lds_dwordx4 v[202:203], off
	v_lshl_add_u64 v[202:203], s[58:59], 0, v[134:135]
	s_mov_b32 m0, s53
	s_nop 0
	global_load_lds_dwordx4 v[202:203], off
	s_mov_b32 m0, s60
	s_nop 0
	global_load_lds_dwordx4 v[248:249], off
	s_waitcnt vmcnt(8)
	s_waitcnt lgkmcnt(0)
	s_barrier
	s_setprio 1
	s_waitcnt lgkmcnt(0)
	v_mfma_f32_16x16x32_bf16 v[62:65], v[146:149], v[178:181], v[62:65]
	v_mfma_f32_16x16x32_bf16 v[58:61], v[154:157], v[178:181], v[58:61]
	v_mfma_f32_16x16x32_bf16 v[46:49], v[146:149], v[224:227], v[46:49]
	v_mfma_f32_16x16x32_bf16 v[42:45], v[154:157], v[224:227], v[42:45]
	v_mfma_f32_16x16x32_bf16 v[30:33], v[146:149], v[232:235], v[30:33]
	v_mfma_f32_16x16x32_bf16 v[26:29], v[154:157], v[232:235], v[26:29]
	v_mfma_f32_16x16x32_bf16 v[14:17], v[146:149], v[240:243], v[14:17]
	v_mfma_f32_16x16x32_bf16 v[10:13], v[154:157], v[240:243], v[10:13]
	v_mfma_f32_16x16x32_bf16 v[62:65], v[150:153], v[182:185], v[62:65]
	v_mfma_f32_16x16x32_bf16 v[58:61], v[158:161], v[182:185], v[58:61]
	v_mfma_f32_16x16x32_bf16 v[46:49], v[150:153], v[228:231], v[46:49]
	v_mfma_f32_16x16x32_bf16 v[42:45], v[158:161], v[228:231], v[42:45]
	v_mfma_f32_16x16x32_bf16 v[30:33], v[150:153], v[236:239], v[30:33]
	v_mfma_f32_16x16x32_bf16 v[26:29], v[158:161], v[236:239], v[26:29]
	v_mfma_f32_16x16x32_bf16 v[14:17], v[150:153], v[244:247], v[14:17]
	v_mfma_f32_16x16x32_bf16 v[10:13], v[158:161], v[244:247], v[10:13]
	s_setprio 0
	s_setprio 1
	v_mfma_f32_16x16x32_bf16 v[54:57], v[162:165], v[178:181], v[54:57]
	v_mfma_f32_16x16x32_bf16 v[50:53], v[170:173], v[178:181], v[50:53]
	v_mfma_f32_16x16x32_bf16 v[38:41], v[162:165], v[224:227], v[38:41]
	v_mfma_f32_16x16x32_bf16 v[34:37], v[170:173], v[224:227], v[34:37]
	v_mfma_f32_16x16x32_bf16 v[22:25], v[162:165], v[232:235], v[22:25]
	v_mfma_f32_16x16x32_bf16 v[18:21], v[170:173], v[232:235], v[18:21]
	v_mfma_f32_16x16x32_bf16 v[6:9], v[162:165], v[240:243], v[6:9]
	v_mfma_f32_16x16x32_bf16 v[2:5], v[170:173], v[240:243], v[2:5]
	v_mfma_f32_16x16x32_bf16 v[54:57], v[166:169], v[182:185], v[54:57]
	v_mfma_f32_16x16x32_bf16 v[50:53], v[174:177], v[182:185], v[50:53]
	v_mfma_f32_16x16x32_bf16 v[38:41], v[166:169], v[228:231], v[38:41]
	v_mfma_f32_16x16x32_bf16 v[34:37], v[174:177], v[228:231], v[34:37]
	v_mfma_f32_16x16x32_bf16 v[22:25], v[166:169], v[236:239], v[22:25]
	v_mfma_f32_16x16x32_bf16 v[18:21], v[174:177], v[236:239], v[18:21]
	v_mfma_f32_16x16x32_bf16 v[6:9], v[166:169], v[244:247], v[6:9]
	v_mfma_f32_16x16x32_bf16 v[2:5], v[174:177], v[244:247], v[2:5]
	s_setprio 0
	s_barrier
	s_add_i32 s10, 0, 0x18000
	s_add_i32 s11, 0, 0x1c000
	v_add_u32_e32 v158, s10, v143
	v_add_u32_e32 v174, s11, v143
	ds_read_b128 v[146:149], v158
	ds_read_b128 v[150:153], v158 offset:1024
	ds_read_b128 v[154:157], v158 offset:2048
	ds_read_b128 v[158:161], v158 offset:3072
	ds_read_b128 v[162:165], v174
	ds_read_b128 v[166:169], v174 offset:1024
	ds_read_b128 v[170:173], v174 offset:2048
	ds_read_b128 v[174:177], v174 offset:3072
	s_add_u32 s8, s58, 0xb0000
	s_addc_u32 s9, s59, 0
	s_mov_b32 m0, s61
	v_lshl_add_u64 v[250:251], s[8:9], 0, v[134:135]
	ds_read_b128 v[178:181], v145 offset:32768
	ds_read_b128 v[182:185], v145 offset:33792
	ds_read_b128 v[224:227], v145 offset:34816
	ds_read_b128 v[228:231], v145 offset:35840
	ds_read_b128 v[232:235], v145 offset:36864
	ds_read_b128 v[236:239], v145 offset:37888
	ds_read_b128 v[240:243], v145 offset:38912
	ds_read_b128 v[244:247], v145 offset:39936
	global_load_lds_dwordx4 v[250:251], off
	v_lshl_add_u64 v[250:251], s[8:9], 0, v[132:133]
	s_mov_b32 m0, s62
	s_nop 0
	global_load_lds_dwordx4 v[250:251], off
	s_and_b32 s96, s74, 7
	s_cmp_lg_u32 s96, 0
	s_cbranch_scc1 .Lg2_tch_skip
	s_cmp_eq_u32 s74, 0
	s_cbranch_scc1 .Lg2_tch_skip
	s_cmp_eq_u32 s74, 40
	s_cbranch_scc1 .Lg2_tch_skip
	s_lshl_b32 s96, s74, 15
	s_sub_u32 s96, s96, 0x40000
	s_lshl_b32 s97, s69, 20
	s_add_u32 s96, s96, s97
	s_lshl_b32 s97, s68, 10
	s_add_u32 s96, s96, s97
	v_lshrrev_b32_e32 v250, 3, v204
	v_and_b32_e32 v251, 7, v204
	v_lshlrev_b32_e32 v250, 12, v250
	v_lshl_or_b32 v250, v251, 7, v250
	v_add_u32_e32 v250, s96, v250
	global_load_dword v251, v250, s[42:43]
.Lg2_tch_skip:
	s_waitcnt vmcnt(8)
	s_waitcnt lgkmcnt(0)
	s_barrier
	s_setprio 1
	s_waitcnt lgkmcnt(0)
	v_mfma_f32_16x16x32_bf16 v[126:129], v[146:149], v[178:181], v[126:129]
	v_mfma_f32_16x16x32_bf16 v[122:125], v[154:157], v[178:181], v[122:125]
	v_mfma_f32_16x16x32_bf16 v[110:113], v[146:149], v[224:227], v[110:113]
	v_mfma_f32_16x16x32_bf16 v[106:109], v[154:157], v[224:227], v[106:109]
	v_mfma_f32_16x16x32_bf16 v[94:97], v[146:149], v[232:235], v[94:97]
	v_mfma_f32_16x16x32_bf16 v[90:93], v[154:157], v[232:235], v[90:93]
	v_mfma_f32_16x16x32_bf16 v[78:81], v[146:149], v[240:243], v[78:81]
	v_mfma_f32_16x16x32_bf16 v[74:77], v[154:157], v[240:243], v[74:77]
	v_mfma_f32_16x16x32_bf16 v[126:129], v[150:153], v[182:185], v[126:129]
	v_mfma_f32_16x16x32_bf16 v[122:125], v[158:161], v[182:185], v[122:125]
	v_mfma_f32_16x16x32_bf16 v[110:113], v[150:153], v[228:231], v[110:113]
	v_mfma_f32_16x16x32_bf16 v[106:109], v[158:161], v[228:231], v[106:109]
	v_mfma_f32_16x16x32_bf16 v[94:97], v[150:153], v[236:239], v[94:97]
	v_mfma_f32_16x16x32_bf16 v[90:93], v[158:161], v[236:239], v[90:93]
	v_mfma_f32_16x16x32_bf16 v[78:81], v[150:153], v[244:247], v[78:81]
	v_mfma_f32_16x16x32_bf16 v[74:77], v[158:161], v[244:247], v[74:77]
	s_setprio 0
	s_setprio 1
	v_mfma_f32_16x16x32_bf16 v[118:121], v[162:165], v[178:181], v[118:121]
	v_mfma_f32_16x16x32_bf16 v[114:117], v[170:173], v[178:181], v[114:117]
	v_mfma_f32_16x16x32_bf16 v[102:105], v[162:165], v[224:227], v[102:105]
	v_mfma_f32_16x16x32_bf16 v[98:101], v[170:173], v[224:227], v[98:101]
	v_mfma_f32_16x16x32_bf16 v[86:89], v[162:165], v[232:235], v[86:89]
	v_mfma_f32_16x16x32_bf16 v[82:85], v[170:173], v[232:235], v[82:85]
	v_mfma_f32_16x16x32_bf16 v[70:73], v[162:165], v[240:243], v[70:73]
	v_mfma_f32_16x16x32_bf16 v[66:69], v[170:173], v[240:243], v[66:69]
	v_mfma_f32_16x16x32_bf16 v[118:121], v[166:169], v[182:185], v[118:121]
	v_mfma_f32_16x16x32_bf16 v[114:117], v[174:177], v[182:185], v[114:117]
	v_mfma_f32_16x16x32_bf16 v[102:105], v[166:169], v[228:231], v[102:105]
	v_mfma_f32_16x16x32_bf16 v[98:101], v[174:177], v[228:231], v[98:101]
	v_mfma_f32_16x16x32_bf16 v[86:89], v[166:169], v[236:239], v[86:89]
	v_mfma_f32_16x16x32_bf16 v[82:85], v[174:177], v[236:239], v[82:85]
	v_mfma_f32_16x16x32_bf16 v[70:73], v[166:169], v[244:247], v[70:73]
	v_mfma_f32_16x16x32_bf16 v[66:69], v[174:177], v[244:247], v[66:69]
	s_setprio 0
	s_barrier
	s_add_i32 s8, s10, s52
	v_lshl_add_u64 v[140:141], v[140:141], 0, s[26:27]
	s_mov_b32 m0, s8
	ds_read_b128 v[178:181], v145 offset:49152
	ds_read_b128 v[182:185], v145 offset:50176
	ds_read_b128 v[224:227], v145 offset:51200
	ds_read_b128 v[228:231], v145 offset:52224
	ds_read_b128 v[232:235], v145 offset:53248
	ds_read_b128 v[236:239], v145 offset:54272
	ds_read_b128 v[240:243], v145 offset:55296
	ds_read_b128 v[244:247], v145 offset:56320
	global_load_lds_dwordx4 v[140:141], off
	s_add_i32 m0, s8, 0x2000
	s_add_u32 s8, s54, 0xb0080
	v_lshl_add_u64 v[140:141], v[186:187], 0, s[26:27]
	s_addc_u32 s9, s55, 0
	s_add_i32 s10, s11, s52
	global_load_lds_dwordx4 v[140:141], off
	v_lshl_add_u64 v[140:141], s[8:9], 0, v[0:1]
	s_mov_b32 m0, s10
	s_nop 0
	global_load_lds_dwordx4 v[140:141], off
	v_lshl_add_u64 v[140:141], s[8:9], 0, v[130:131]
	s_add_i32 m0, s10, 0x2000
	s_nop 0
	global_load_lds_dwordx4 v[140:141], off
	v_lshl_add_u64 v[140:141], v[202:203], 0, s[26:27]
	s_mov_b32 m0, s63
	s_nop 0
	global_load_lds_dwordx4 v[140:141], off
	v_lshl_add_u64 v[140:141], v[248:249], 0, s[26:27]
	s_mov_b32 m0, s64
	s_nop 0
	global_load_lds_dwordx4 v[140:141], off
	s_waitcnt vmcnt(8)
	s_waitcnt lgkmcnt(0)
	s_barrier
	s_setprio 1
	s_waitcnt lgkmcnt(0)
	v_mfma_f32_16x16x32_bf16 v[62:65], v[146:149], v[178:181], v[62:65]
	v_mfma_f32_16x16x32_bf16 v[58:61], v[154:157], v[178:181], v[58:61]
	v_mfma_f32_16x16x32_bf16 v[46:49], v[146:149], v[224:227], v[46:49]
	v_mfma_f32_16x16x32_bf16 v[42:45], v[154:157], v[224:227], v[42:45]
	v_mfma_f32_16x16x32_bf16 v[30:33], v[146:149], v[232:235], v[30:33]
	v_mfma_f32_16x16x32_bf16 v[26:29], v[154:157], v[232:235], v[26:29]
	v_mfma_f32_16x16x32_bf16 v[14:17], v[146:149], v[240:243], v[14:17]
	v_mfma_f32_16x16x32_bf16 v[10:13], v[154:157], v[240:243], v[10:13]
	v_mfma_f32_16x16x32_bf16 v[62:65], v[150:153], v[182:185], v[62:65]
	v_mfma_f32_16x16x32_bf16 v[58:61], v[158:161], v[182:185], v[58:61]
	v_mfma_f32_16x16x32_bf16 v[46:49], v[150:153], v[228:231], v[46:49]
	v_mfma_f32_16x16x32_bf16 v[42:45], v[158:161], v[228:231], v[42:45]
	v_mfma_f32_16x16x32_bf16 v[30:33], v[150:153], v[236:239], v[30:33]
	v_mfma_f32_16x16x32_bf16 v[26:29], v[158:161], v[236:239], v[26:29]
	v_mfma_f32_16x16x32_bf16 v[14:17], v[150:153], v[244:247], v[14:17]
	v_mfma_f32_16x16x32_bf16 v[10:13], v[158:161], v[244:247], v[10:13]
	s_setprio 0
	s_setprio 1
	v_mfma_f32_16x16x32_bf16 v[54:57], v[162:165], v[178:181], v[54:57]
	v_mfma_f32_16x16x32_bf16 v[50:53], v[170:173], v[178:181], v[50:53]
	v_mfma_f32_16x16x32_bf16 v[38:41], v[162:165], v[224:227], v[38:41]
	v_mfma_f32_16x16x32_bf16 v[34:37], v[170:173], v[224:227], v[34:37]
	v_mfma_f32_16x16x32_bf16 v[22:25], v[162:165], v[232:235], v[22:25]
	v_mfma_f32_16x16x32_bf16 v[18:21], v[170:173], v[232:235], v[18:21]
	v_mfma_f32_16x16x32_bf16 v[6:9], v[162:165], v[240:243], v[6:9]
	v_mfma_f32_16x16x32_bf16 v[2:5], v[170:173], v[240:243], v[2:5]
	v_mfma_f32_16x16x32_bf16 v[54:57], v[166:169], v[182:185], v[54:57]
	v_mfma_f32_16x16x32_bf16 v[50:53], v[174:177], v[182:185], v[50:53]
	v_mfma_f32_16x16x32_bf16 v[38:41], v[166:169], v[228:231], v[38:41]
	v_mfma_f32_16x16x32_bf16 v[34:37], v[174:177], v[228:231], v[34:37]
	v_mfma_f32_16x16x32_bf16 v[22:25], v[166:169], v[236:239], v[22:25]
	v_mfma_f32_16x16x32_bf16 v[18:21], v[174:177], v[236:239], v[18:21]
	v_mfma_f32_16x16x32_bf16 v[6:9], v[166:169], v[244:247], v[6:9]
	v_mfma_f32_16x16x32_bf16 v[2:5], v[174:177], v[244:247], v[2:5]
	s_setprio 0
	s_barrier
	s_add_i32 s74, s74, 2
	s_add_u32 s72, s72, 0x100
	s_addc_u32 s73, s73, 0
	s_cmp_gt_u32 s74, 41
	s_mov_b64 s[50:51], s[56:57]
	s_cbranch_scc0 .LBB0_535
	s_and_b64 vcc, exec, s[46:47]
	s_cbranch_vccz .LBB0_538
	s_barrier
